# stack7 plus peeled first K iteration uses vmcnt(24) for its first two waits when epilogue stores precede it (stores no longer gate the first two phases)
# speedup vs baseline: 1.0024x; 1.0024x over previous
; #define PG8_STAGE(bufoff, gbase, v0, dv) do { _Pragma("unroll") for (int _i = 0; _i < 2; ++_i) \
;         __builtin_amdgcn_global_load_lds((const unsigned*)((const char*)(gbase) + ((v0) + (unsigned)_i * (dv))), (PG8_LAS unsigned*)(lds + (bufoff) + ldsw + _i * 8192), 16, 0, 0); } while (0)
; #define PG8_LDA(dst, b, h) do { _Pragma("unroll") for (int m = 0; m < 4; ++m) _Pragma("unroll") for (int k = 0; k < 2; ++k) dst[m][k] = *(const PG8_LAS bf16x8*)(lds + PG8_SA(b, h) + aoff + m * 2048 + k * 1024); } while (0)
; #define PG8_LDB(dst, b, h) do { _Pragma("unroll") for (int n = 0; n < 2; ++n) _Pragma("unroll") for (int k = 0; k < 2; ++k) dst[n][k] = *(const PG8_LAS bf16x8*)(lds + PG8_SB(b, h) + boff + n * 2048 + k * 1024); } while (0)
; #define PG8_MMA(ai, bj, At, Bt) do { __builtin_amdgcn_s_setprio(1); _Pragma("unroll") for (int m = 0; m < 4; ++m) _Pragma("unroll") for (int n = 0; n < 2; ++n) _Pragma("unroll") for (int k = 0; k < 2; ++k) \
;         acc[ai][bj][m][n] = __builtin_amdgcn_mfma_f32_16x16x32_bf16(Bt[n][k], At[m][k], acc[ai][bj][m][n], 0, 0, 0); __builtin_amdgcn_s_setprio(0); } while (0)
; template <class Epi, class Sched, bool MERGE>
; __device__ __forceinline__ void gemm_stream(PG8_LAS unsigned char* lds, const Sched& S, const Epi& E) {
;     ...
;         const int nt = cur.K / BK; const unsigned ck2 = (unsigned)(2 * cur.K), nk2 = (unsigned)(2 * nxt.K);
;         for (int t = 0; t < nt; t += 2) {
;             const bool last = (t == nt - 2);
;             const char* a1 = cA + (size_t)(t + 1) * kstep;
;             const char* a2 = last ? nA : cA + (size_t)(t + 2) * kstep; const char* b2 = last ? nB : cB + (size_t)(t + 2) * kstep;
;             const char* a3 = a2 + kstep; const char* b3 = b2 + kstep;
;             const size_t hs2 = last ? nhs : chs;
;             const unsigned k2b = last ? nk2 : ck2;
;             const unsigned cvA = rA0 * ck2 + c20, cdv = 64u * ck2, vA2 = rA0 * k2b + c20, vB2 = rB0 * k2b + c20, dv2 = 64u * k2b;
;             PG8_LDB(B0, 0, 0); PG8_LDB(B1, 0, 1); PG8_SCHED; PG8_LDA(At, 0, 0); PG8_STAGE(PG8_SA(1, 1), a1 + chs, cvA, cdv);
;             PG8_WAIT_V(8); PG8_WAIT_L(0); PG8_BAR; PG8_MMA(0, 0, At, B0); PG8_MMA(0, 1, At, B1); PG8_BAR; PG8_SCHED;
;             PG8_LDA(At, 0, 1); PG8_STAGE(PG8_SB(0, 0), b2, vB2, dv2); PG8_STAGE(PG8_SB(0, 1), b2 + hs2, vB2, dv2); PG8_STAGE(PG8_SA(0, 0), a2, vA2, dv2);
.LBB0_235:
	s_ashr_i32 s27, s26, 31
	s_lshl_b64 s[28:29], s[26:27], 8
	v_mov_b32_e32 v127, 0
	s_cmp_lt_i32 s61, 64
	s_cbranch_scc1 .LBB0_238
	s_ashr_i32 s6, s61, 31
	s_lshr_b32 s6, s6, 26
	s_add_i32 s6, s61, s6
	s_ashr_i32 s27, s6, 6
	s_lshl_b32 s46, s61, 1
	s_lshl_b32 s47, s26, 1
	s_add_i32 s59, s27, -2
	s_add_u32 s6, s34, 0x80
	s_addc_u32 s7, s35, 0
	v_mad_u64_u32 v[0:1], s[34:35], s46, v137, v[144:145]
	v_mov_b32_e32 v1, v179
	v_lshl_add_u64 v[128:129], s[30:31], 0, v[0:1]
	v_mad_u64_u32 v[0:1], s[34:35], v164, s61, v[144:145]
	v_mov_b32_e32 v1, v179
	s_add_u32 s73, s36, 0x100
	v_lshl_add_u64 v[130:131], s[30:31], 0, v[0:1]
	s_addc_u32 s94, s37, 0
	s_mov_b32 vcc_lo, 0
	s_cmp_eq_u32 s59, vcc_lo
	s_cselect_b64 s[36:37], -1, 0
	s_add_i32 vcc_lo, vcc_lo, 2
	s_add_u32 s50, s6, 0x80
	s_addc_u32 s51, s7, 0
	s_and_b64 s[34:35], s[36:37], exec
	s_cselect_b32 s35, s23, s51
	s_cselect_b32 s34, s22, s50
	s_cselect_b32 s58, s47, s46
	s_cselect_b32 s61, s29, s31
	s_cselect_b32 vcc_hi, s28, s30
	s_add_i32 s96, 0, 0x10000
	v_mad_u64_u32 v[174:175], s[50:51], s58, v139, v[136:137]
	s_and_b64 s[36:37], s[36:37], exec
	v_mad_u64_u32 v[224:225], s[50:51], s58, v137, v[136:137]
	s_cselect_b32 s37, s25, s94
	s_cselect_b32 s36, s24, s73
	s_add_i32 s50, 0, 0x14000
	v_add_u32_e32 v154, s96, v162
	v_add_u32_e32 v175, s50, v162
	ds_read_b128 v[132:135], v154
	ds_read_b128 v[146:149], v154 offset:1024
	ds_read_b128 v[150:153], v154 offset:2048
	ds_read_b128 v[154:157], v154 offset:3072
	ds_read_b128 v[158:161], v175
	ds_read_b128 v[166:169], v175 offset:1024
	ds_read_b128 v[170:173], v175 offset:2048
	ds_read_b128 v[180:183], v175 offset:3072
	v_lshl_add_u64 v[230:231], s[6:7], 0, v[128:129]
	s_add_i32 m0, s66, 0xc000
	ds_read_b128 v[192:195], v165
	ds_read_b128 v[196:199], v165 offset:1024
	ds_read_b128 v[200:203], v165 offset:2048
	ds_read_b128 v[204:207], v165 offset:3072
	ds_read_b128 v[208:211], v165 offset:4096
	ds_read_b128 v[212:215], v165 offset:5120
	ds_read_b128 v[216:219], v165 offset:6144
	ds_read_b128 v[220:223], v165 offset:7168
	global_load_lds_dwordx4 v[230:231], off
	v_lshl_add_u64 v[230:231], s[6:7], 0, v[130:131]
	s_add_i32 m0, s66, 0xe000
	s_nop 0
	global_load_lds_dwordx4 v[230:231], off
	s_cmp_eq_u32 s42, 1
	s_cbranch_scc1 .Lpeelw8_1
	s_waitcnt vmcnt(24)
	s_branch .Lpeelwd_1
.Lpeelw8_1:
	s_waitcnt vmcnt(8)
.Lpeelwd_1:
	s_waitcnt lgkmcnt(0)
	s_barrier
	s_setprio 1
	s_waitcnt lgkmcnt(0)
	v_mfma_f32_16x16x32_bf16 v[124:127], v[132:135], v[192:195], 0
	v_mfma_f32_16x16x32_bf16 v[120:123], v[150:153], v[192:195], 0
	v_mfma_f32_16x16x32_bf16 v[108:111], v[132:135], v[200:203], 0
	v_mfma_f32_16x16x32_bf16 v[104:107], v[150:153], v[200:203], 0
	v_mfma_f32_16x16x32_bf16 v[92:95], v[132:135], v[208:211], 0
	v_mfma_f32_16x16x32_bf16 v[88:91], v[150:153], v[208:211], 0
	v_mfma_f32_16x16x32_bf16 v[76:79], v[132:135], v[216:219], 0
	v_mfma_f32_16x16x32_bf16 v[72:75], v[150:153], v[216:219], 0
	v_mfma_f32_16x16x32_bf16 v[124:127], v[146:149], v[196:199], v[124:127]
	v_mfma_f32_16x16x32_bf16 v[120:123], v[154:157], v[196:199], v[120:123]
	v_mfma_f32_16x16x32_bf16 v[108:111], v[146:149], v[204:207], v[108:111]
	v_mfma_f32_16x16x32_bf16 v[104:107], v[154:157], v[204:207], v[104:107]
	v_mfma_f32_16x16x32_bf16 v[92:95], v[146:149], v[212:215], v[92:95]
	v_mfma_f32_16x16x32_bf16 v[88:91], v[154:157], v[212:215], v[88:91]
	v_mfma_f32_16x16x32_bf16 v[76:79], v[146:149], v[220:223], v[76:79]
	v_mfma_f32_16x16x32_bf16 v[72:75], v[154:157], v[220:223], v[72:75]
	s_setprio 0
	s_setprio 1
	v_mfma_f32_16x16x32_bf16 v[116:119], v[158:161], v[192:195], 0
	v_mfma_f32_16x16x32_bf16 v[112:115], v[170:173], v[192:195], 0
	v_mfma_f32_16x16x32_bf16 v[100:103], v[158:161], v[200:203], 0
	v_mfma_f32_16x16x32_bf16 v[96:99], v[170:173], v[200:203], 0
	v_mfma_f32_16x16x32_bf16 v[84:87], v[158:161], v[208:211], 0
	v_mfma_f32_16x16x32_bf16 v[80:83], v[170:173], v[208:211], 0
	v_mfma_f32_16x16x32_bf16 v[68:71], v[158:161], v[216:219], 0
	v_mfma_f32_16x16x32_bf16 v[64:67], v[170:173], v[216:219], 0
	v_mfma_f32_16x16x32_bf16 v[116:119], v[166:169], v[196:199], v[116:119]
	v_mfma_f32_16x16x32_bf16 v[112:115], v[180:183], v[196:199], v[112:115]
	v_mfma_f32_16x16x32_bf16 v[100:103], v[166:169], v[204:207], v[100:103]
	v_mfma_f32_16x16x32_bf16 v[96:99], v[180:183], v[204:207], v[96:99]
	v_mfma_f32_16x16x32_bf16 v[84:87], v[166:169], v[212:215], v[84:87]
	v_mfma_f32_16x16x32_bf16 v[80:83], v[180:183], v[212:215], v[80:83]
	v_mfma_f32_16x16x32_bf16 v[68:71], v[166:169], v[220:223], v[68:71]
	v_mfma_f32_16x16x32_bf16 v[64:67], v[180:183], v[220:223], v[64:67]
	s_setprio 0
	s_barrier
	s_lshl_b32 s51, s58, 6
	s_add_i32 s58, s96, s65
	s_mov_b32 m0, s58
	ds_read_b128 v[192:195], v165 offset:16384
	ds_read_b128 v[196:199], v165 offset:17408
	ds_read_b128 v[200:203], v165 offset:18432
	ds_read_b128 v[204:207], v165 offset:19456
	ds_read_b128 v[208:211], v165 offset:20480
	ds_read_b128 v[212:215], v165 offset:21504
	ds_read_b128 v[216:219], v165 offset:22528
	ds_read_b128 v[220:223], v165 offset:23552
	v_mov_b32_e32 v175, v179
	global_load_lds_dwordx4 v174, s[36:37]
	v_add_u32_e32 v178, s51, v174
	s_add_i32 m0, s58, 0x2000
	v_lshl_add_u64 v[230:231], s[36:37], 0, v[174:175]
	v_lshl_add_u64 v[232:233], s[36:37], 0, v[178:179]
	global_load_lds_dwordx4 v178, s[36:37]
	s_add_u32 s36, s36, vcc_hi
	s_addc_u32 s37, s37, s61
	s_add_i32 s50, s50, s65
	s_mov_b32 m0, s50
	v_lshl_add_u64 v[234:235], s[36:37], 0, v[174:175]
	global_load_lds_dwordx4 v174, s[36:37]
	s_add_i32 m0, s50, 0x2000
	v_lshl_add_u64 v[174:175], s[36:37], 0, v[178:179]
	global_load_lds_dwordx4 v178, s[36:37]
	s_mov_b32 m0, s66
	v_add_u32_e32 v178, s51, v224
	global_load_lds_dwordx4 v224, s[34:35]
	s_mov_b32 m0, s67
	v_mov_b32_e32 v225, v179
	global_load_lds_dwordx4 v178, s[34:35]
	s_cmp_eq_u32 s42, 1
	s_cbranch_scc1 .Lpeelw8_2
	s_waitcnt vmcnt(24)
	s_branch .Lpeelwd_2

; #define PG8_STAGE(bufoff, gbase, v0, dv) do { _Pragma("unroll") for (int _i = 0; _i < 2; ++_i) \
;         __builtin_amdgcn_global_load_lds((const unsigned*)((const char*)(gbase) + ((v0) + (unsigned)_i * (dv))), (PG8_LAS unsigned*)(lds + (bufoff) + ldsw + _i * 8192), 16, 0, 0); } while (0)
; #define PG8_LDA(dst, b, h) do { _Pragma("unroll") for (int m = 0; m < 4; ++m) _Pragma("unroll") for (int k = 0; k < 2; ++k) dst[m][k] = *(const PG8_LAS bf16x8*)(lds + PG8_SA(b, h) + aoff + m * 2048 + k * 1024); } while (0)
; #define PG8_LDB(dst, b, h) do { _Pragma("unroll") for (int n = 0; n < 2; ++n) _Pragma("unroll") for (int k = 0; k < 2; ++k) dst[n][k] = *(const PG8_LAS bf16x8*)(lds + PG8_SB(b, h) + boff + n * 2048 + k * 1024); } while (0)
; #define PG8_MMA(ai, bj, At, Bt) do { __builtin_amdgcn_s_setprio(1); _Pragma("unroll") for (int m = 0; m < 4; ++m) _Pragma("unroll") for (int n = 0; n < 2; ++n) _Pragma("unroll") for (int k = 0; k < 2; ++k) \
;         acc[ai][bj][m][n] = __builtin_amdgcn_mfma_f32_16x16x32_bf16(Bt[n][k], At[m][k], acc[ai][bj][m][n], 0, 0, 0); __builtin_amdgcn_s_setprio(0); } while (0)
; #define PG8_WAIT_V(n) asm volatile("s_waitcnt vmcnt(" #n ")" ::: "memory")
; #define PG8_WAIT_L(n) asm volatile("s_waitcnt lgkmcnt(" #n ")" ::: "memory")
; #define PG8_BAR __builtin_amdgcn_s_barrier()
; #define PG8_SCHED __builtin_amdgcn_sched_barrier(0)
; template <class Epi, class Sched, bool MERGE>
; __device__ __forceinline__ void gemm_stream(PG8_LAS unsigned char* lds, const Sched& S, const Epi& E) {
;     ...
;             PG8_WAIT_V(8); PG8_WAIT_L(0); PG8_BAR; PG8_MMA(1, 0, At, B0); PG8_MMA(1, 1, At, B1); PG8_BAR; PG8_SCHED;
;             PG8_LDB(B0, 1, 0); PG8_LDB(B1, 1, 1); PG8_SCHED; PG8_LDA(At, 1, 0); PG8_STAGE(PG8_SA(0, 1), a2 + hs2, vA2, dv2);
;             PG8_WAIT_V(8); PG8_WAIT_L(0); PG8_BAR; PG8_MMA(0, 0, At, B0); PG8_MMA(0, 1, At, B1); PG8_BAR; PG8_SCHED;
.Lpeelwd_2:
	s_waitcnt lgkmcnt(0)
	v_lshl_add_u64 v[236:237], s[34:35], 0, v[224:225]
	v_lshl_add_u64 v[238:239], s[34:35], 0, v[178:179]
	s_barrier
	s_setprio 1
	s_waitcnt lgkmcnt(0)
	v_mfma_f32_16x16x32_bf16 v[60:63], v[132:135], v[192:195], 0
	v_mfma_f32_16x16x32_bf16 v[56:59], v[150:153], v[192:195], 0
	v_mfma_f32_16x16x32_bf16 v[44:47], v[132:135], v[200:203], 0
	v_mfma_f32_16x16x32_bf16 v[40:43], v[150:153], v[200:203], 0
	v_mfma_f32_16x16x32_bf16 v[28:31], v[132:135], v[208:211], 0
	v_mfma_f32_16x16x32_bf16 v[24:27], v[150:153], v[208:211], 0
	v_mfma_f32_16x16x32_bf16 v[12:15], v[132:135], v[216:219], 0
	v_mfma_f32_16x16x32_bf16 v[8:11], v[150:153], v[216:219], 0
	v_mfma_f32_16x16x32_bf16 v[60:63], v[146:149], v[196:199], v[60:63]
	v_mfma_f32_16x16x32_bf16 v[56:59], v[154:157], v[196:199], v[56:59]
	v_mfma_f32_16x16x32_bf16 v[44:47], v[146:149], v[204:207], v[44:47]
	v_mfma_f32_16x16x32_bf16 v[40:43], v[154:157], v[204:207], v[40:43]
	v_mfma_f32_16x16x32_bf16 v[28:31], v[146:149], v[212:215], v[28:31]
	v_mfma_f32_16x16x32_bf16 v[24:27], v[154:157], v[212:215], v[24:27]
	v_mfma_f32_16x16x32_bf16 v[12:15], v[146:149], v[220:223], v[12:15]
	v_mfma_f32_16x16x32_bf16 v[8:11], v[154:157], v[220:223], v[8:11]
	s_setprio 0
	s_setprio 1
	v_mfma_f32_16x16x32_bf16 v[52:55], v[158:161], v[192:195], 0
	v_mfma_f32_16x16x32_bf16 v[48:51], v[170:173], v[192:195], 0
	v_mfma_f32_16x16x32_bf16 v[36:39], v[158:161], v[200:203], 0
	v_mfma_f32_16x16x32_bf16 v[32:35], v[170:173], v[200:203], 0
	v_mfma_f32_16x16x32_bf16 v[20:23], v[158:161], v[208:211], 0
	v_mfma_f32_16x16x32_bf16 v[16:19], v[170:173], v[208:211], 0
	v_mfma_f32_16x16x32_bf16 v[4:7], v[158:161], v[216:219], 0
	v_mfma_f32_16x16x32_bf16 v[0:3], v[170:173], v[216:219], 0
	v_mfma_f32_16x16x32_bf16 v[52:55], v[166:169], v[196:199], v[52:55]
	v_mfma_f32_16x16x32_bf16 v[48:51], v[180:183], v[196:199], v[48:51]
	v_mfma_f32_16x16x32_bf16 v[36:39], v[166:169], v[204:207], v[36:39]
	v_mfma_f32_16x16x32_bf16 v[32:35], v[180:183], v[204:207], v[32:35]
	v_mfma_f32_16x16x32_bf16 v[20:23], v[166:169], v[212:215], v[20:23]
	v_mfma_f32_16x16x32_bf16 v[16:19], v[180:183], v[212:215], v[16:19]
	v_mfma_f32_16x16x32_bf16 v[4:7], v[166:169], v[220:223], v[4:7]
	v_mfma_f32_16x16x32_bf16 v[0:3], v[180:183], v[220:223], v[0:3]
	s_setprio 0
	s_barrier
	s_add_i32 s36, 0, 0x18000
	s_add_i32 s37, 0, 0x1c000
	v_add_u32_e32 v154, s36, v162
	v_add_u32_e32 v180, s37, v162
	ds_read_b128 v[132:135], v154
	ds_read_b128 v[146:149], v154 offset:1024
	ds_read_b128 v[150:153], v154 offset:2048
	ds_read_b128 v[154:157], v154 offset:3072
	ds_read_b128 v[158:161], v180
	ds_read_b128 v[166:169], v180 offset:1024
	ds_read_b128 v[170:173], v180 offset:2048
	ds_read_b128 v[180:183], v180 offset:3072
	s_add_u32 s34, s34, vcc_hi
	s_addc_u32 s35, s35, s61
	s_mov_b32 m0, s68
	ds_read_b128 v[192:195], v165 offset:32768
	ds_read_b128 v[196:199], v165 offset:33792
	ds_read_b128 v[200:203], v165 offset:34816
	ds_read_b128 v[204:207], v165 offset:35840
	ds_read_b128 v[208:211], v165 offset:36864
	ds_read_b128 v[212:215], v165 offset:37888
	ds_read_b128 v[216:219], v165 offset:38912
	ds_read_b128 v[220:223], v165 offset:39936
	global_load_lds_dwordx4 v224, s[34:35]
	s_mov_b32 m0, s69
	s_nop 0
	global_load_lds_dwordx4 v178, s[34:35]
	s_waitcnt vmcnt(8)
	s_waitcnt lgkmcnt(0)
	s_barrier
	s_setprio 1
	s_waitcnt lgkmcnt(0)
	v_mfma_f32_16x16x32_bf16 v[124:127], v[132:135], v[192:195], v[124:127]
	v_mfma_f32_16x16x32_bf16 v[120:123], v[150:153], v[192:195], v[120:123]
	v_mfma_f32_16x16x32_bf16 v[108:111], v[132:135], v[200:203], v[108:111]
	v_mfma_f32_16x16x32_bf16 v[104:107], v[150:153], v[200:203], v[104:107]
	v_mfma_f32_16x16x32_bf16 v[92:95], v[132:135], v[208:211], v[92:95]
	v_mfma_f32_16x16x32_bf16 v[88:91], v[150:153], v[208:211], v[88:91]
	v_mfma_f32_16x16x32_bf16 v[76:79], v[132:135], v[216:219], v[76:79]
	v_mfma_f32_16x16x32_bf16 v[72:75], v[150:153], v[216:219], v[72:75]
	v_mfma_f32_16x16x32_bf16 v[124:127], v[146:149], v[196:199], v[124:127]
	v_mfma_f32_16x16x32_bf16 v[120:123], v[154:157], v[196:199], v[120:123]
	v_mfma_f32_16x16x32_bf16 v[108:111], v[146:149], v[204:207], v[108:111]
	v_mfma_f32_16x16x32_bf16 v[104:107], v[154:157], v[204:207], v[104:107]
	v_mfma_f32_16x16x32_bf16 v[92:95], v[146:149], v[212:215], v[92:95]
	v_mfma_f32_16x16x32_bf16 v[88:91], v[154:157], v[212:215], v[88:91]
	v_mfma_f32_16x16x32_bf16 v[76:79], v[146:149], v[220:223], v[76:79]
	v_mfma_f32_16x16x32_bf16 v[72:75], v[154:157], v[220:223], v[72:75]
	s_setprio 0
	s_setprio 1
	v_mfma_f32_16x16x32_bf16 v[116:119], v[158:161], v[192:195], v[116:119]
	v_mfma_f32_16x16x32_bf16 v[112:115], v[170:173], v[192:195], v[112:115]
	v_mfma_f32_16x16x32_bf16 v[100:103], v[158:161], v[200:203], v[100:103]
	v_mfma_f32_16x16x32_bf16 v[96:99], v[170:173], v[200:203], v[96:99]
	v_mfma_f32_16x16x32_bf16 v[84:87], v[158:161], v[208:211], v[84:87]
	v_mfma_f32_16x16x32_bf16 v[80:83], v[170:173], v[208:211], v[80:83]
	v_mfma_f32_16x16x32_bf16 v[68:71], v[158:161], v[216:219], v[68:71]
	v_mfma_f32_16x16x32_bf16 v[64:67], v[170:173], v[216:219], v[64:67]
	v_mfma_f32_16x16x32_bf16 v[116:119], v[166:169], v[196:199], v[116:119]
	v_mfma_f32_16x16x32_bf16 v[112:115], v[180:183], v[196:199], v[112:115]
	v_mfma_f32_16x16x32_bf16 v[100:103], v[166:169], v[204:207], v[100:103]
	v_mfma_f32_16x16x32_bf16 v[96:99], v[180:183], v[204:207], v[96:99]
	v_mfma_f32_16x16x32_bf16 v[84:87], v[166:169], v[212:215], v[84:87]
	v_mfma_f32_16x16x32_bf16 v[80:83], v[180:183], v[212:215], v[80:83]
	v_mfma_f32_16x16x32_bf16 v[68:71], v[166:169], v[220:223], v[68:71]
	v_mfma_f32_16x16x32_bf16 v[64:67], v[180:183], v[220:223], v[64:67]
	s_setprio 0
	s_barrier
; #define PG8_STAGE(bufoff, gbase, v0, dv) do { _Pragma("unroll") for (int _i = 0; _i < 2; ++_i) \
;         __builtin_amdgcn_global_load_lds((const unsigned*)((const char*)(gbase) + ((v0) + (unsigned)_i * (dv))), (PG8_LAS unsigned*)(lds + (bufoff) + ldsw + _i * 8192), 16, 0, 0); } while (0)
; #define PG8_LDA(dst, b, h) do { _Pragma("unroll") for (int m = 0; m < 4; ++m) _Pragma("unroll") for (int k = 0; k < 2; ++k) dst[m][k] = *(const PG8_LAS bf16x8*)(lds + PG8_SA(b, h) + aoff + m * 2048 + k * 1024); } while (0)
; #define PG8_MMA(ai, bj, At, Bt) do { __builtin_amdgcn_s_setprio(1); _Pragma("unroll") for (int m = 0; m < 4; ++m) _Pragma("unroll") for (int n = 0; n < 2; ++n) _Pragma("unroll") for (int k = 0; k < 2; ++k) \
;         acc[ai][bj][m][n] = __builtin_amdgcn_mfma_f32_16x16x32_bf16(Bt[n][k], At[m][k], acc[ai][bj][m][n], 0, 0, 0); __builtin_amdgcn_s_setprio(0); } while (0)
; #define PG8_WAIT_V(n) asm volatile("s_waitcnt vmcnt(" #n ")" ::: "memory")
; #define PG8_WAIT_L(n) asm volatile("s_waitcnt lgkmcnt(" #n ")" ::: "memory")
; #define PG8_BAR __builtin_amdgcn_s_barrier()
; #define PG8_SCHED __builtin_amdgcn_sched_barrier(0)
; template <class Epi, class Sched, bool MERGE>
; __device__ __forceinline__ void gemm_stream(PG8_LAS unsigned char* lds, const Sched& S, const Epi& E) {
;     ...
;             PG8_LDA(At, 1, 1); PG8_STAGE(PG8_SB(1, 0), b3, vB2, dv2); PG8_STAGE(PG8_SB(1, 1), b3 + hs2, vB2, dv2); PG8_STAGE(PG8_SA(1, 0), a3, vA2, dv2);
;             PG8_WAIT_V(8); PG8_WAIT_L(0); PG8_BAR; PG8_MMA(1, 0, At, B0); PG8_MMA(1, 1, At, B1); PG8_BAR; PG8_SCHED;
;         }
	s_add_i32 s34, s36, s65
	v_lshl_add_u64 v[224:225], v[230:231], 0, s[48:49]
	s_mov_b32 m0, s34
	ds_read_b128 v[192:195], v165 offset:49152
	ds_read_b128 v[196:199], v165 offset:50176
	ds_read_b128 v[200:203], v165 offset:51200
	ds_read_b128 v[204:207], v165 offset:52224
	ds_read_b128 v[208:211], v165 offset:53248
	ds_read_b128 v[212:215], v165 offset:54272
	ds_read_b128 v[216:219], v165 offset:55296
	ds_read_b128 v[220:223], v165 offset:56320
	global_load_lds_dwordx4 v[224:225], off
	v_lshl_add_u64 v[224:225], v[232:233], 0, s[48:49]
	s_add_i32 m0, s34, 0x2000
	s_add_i32 s34, s37, s65
	global_load_lds_dwordx4 v[224:225], off
	v_lshl_add_u64 v[224:225], v[234:235], 0, s[48:49]
	s_mov_b32 m0, s34
	v_lshl_add_u64 v[174:175], v[174:175], 0, s[48:49]
	global_load_lds_dwordx4 v[224:225], off
	s_add_i32 m0, s34, 0x2000
	s_nop 0
	global_load_lds_dwordx4 v[174:175], off
	v_lshl_add_u64 v[174:175], v[236:237], 0, s[48:49]
	s_mov_b32 m0, s71
	s_nop 0
	global_load_lds_dwordx4 v[174:175], off
	v_lshl_add_u64 v[174:175], v[238:239], 0, s[48:49]
	s_mov_b32 m0, s74
	s_nop 0
	global_load_lds_dwordx4 v[174:175], off
	s_waitcnt vmcnt(8)
	s_waitcnt lgkmcnt(0)
	s_barrier
	s_setprio 1
	s_waitcnt lgkmcnt(0)
	v_mfma_f32_16x16x32_bf16 v[60:63], v[132:135], v[192:195], v[60:63]
	v_mfma_f32_16x16x32_bf16 v[56:59], v[150:153], v[192:195], v[56:59]
	v_mfma_f32_16x16x32_bf16 v[44:47], v[132:135], v[200:203], v[44:47]
	v_mfma_f32_16x16x32_bf16 v[40:43], v[150:153], v[200:203], v[40:43]
	v_mfma_f32_16x16x32_bf16 v[28:31], v[132:135], v[208:211], v[28:31]
	v_mfma_f32_16x16x32_bf16 v[24:27], v[150:153], v[208:211], v[24:27]
	v_mfma_f32_16x16x32_bf16 v[12:15], v[132:135], v[216:219], v[12:15]
	v_mfma_f32_16x16x32_bf16 v[8:11], v[150:153], v[216:219], v[8:11]
	v_mfma_f32_16x16x32_bf16 v[60:63], v[146:149], v[196:199], v[60:63]
	v_mfma_f32_16x16x32_bf16 v[56:59], v[154:157], v[196:199], v[56:59]
	v_mfma_f32_16x16x32_bf16 v[44:47], v[146:149], v[204:207], v[44:47]
	v_mfma_f32_16x16x32_bf16 v[40:43], v[154:157], v[204:207], v[40:43]
	v_mfma_f32_16x16x32_bf16 v[28:31], v[146:149], v[212:215], v[28:31]
	v_mfma_f32_16x16x32_bf16 v[24:27], v[154:157], v[212:215], v[24:27]
	v_mfma_f32_16x16x32_bf16 v[12:15], v[146:149], v[220:223], v[12:15]
	v_mfma_f32_16x16x32_bf16 v[8:11], v[154:157], v[220:223], v[8:11]
	s_setprio 0
	s_setprio 1
	v_mfma_f32_16x16x32_bf16 v[52:55], v[158:161], v[192:195], v[52:55]
	v_mfma_f32_16x16x32_bf16 v[48:51], v[170:173], v[192:195], v[48:51]
	v_mfma_f32_16x16x32_bf16 v[36:39], v[158:161], v[200:203], v[36:39]
	v_mfma_f32_16x16x32_bf16 v[32:35], v[170:173], v[200:203], v[32:35]
	v_mfma_f32_16x16x32_bf16 v[20:23], v[158:161], v[208:211], v[20:23]
	v_mfma_f32_16x16x32_bf16 v[16:19], v[170:173], v[208:211], v[16:19]
	v_mfma_f32_16x16x32_bf16 v[4:7], v[158:161], v[216:219], v[4:7]
	v_mfma_f32_16x16x32_bf16 v[0:3], v[170:173], v[216:219], v[0:3]
	v_mfma_f32_16x16x32_bf16 v[52:55], v[166:169], v[196:199], v[52:55]
	v_mfma_f32_16x16x32_bf16 v[48:51], v[180:183], v[196:199], v[48:51]
	v_mfma_f32_16x16x32_bf16 v[36:39], v[166:169], v[204:207], v[36:39]
	v_mfma_f32_16x16x32_bf16 v[32:35], v[180:183], v[204:207], v[32:35]
	v_mfma_f32_16x16x32_bf16 v[20:23], v[166:169], v[212:215], v[20:23]
	v_mfma_f32_16x16x32_bf16 v[16:19], v[180:183], v[212:215], v[16:19]
	v_mfma_f32_16x16x32_bf16 v[4:7], v[166:169], v[220:223], v[4:7]
	v_mfma_f32_16x16x32_bf16 v[0:3], v[180:183], v[220:223], v[0:3]
	s_setprio 0
	s_barrier
	s_add_u32 s6, s6, 0x100
	s_addc_u32 s7, s7, 0
	s_add_u32 s73, s73, 0x100
	s_addc_u32 s94, s94, 0
	s_cmp_ge_i32 vcc_lo, s27
	s_cbranch_scc1 .LBB0_238
